# K-loop: s_setprio 1 raised before the load segment's closing wait, s_setprio 0 lowered after the compute segment's closing barrier (no priority instruction between barrier and MFMAs)
# speedup vs baseline: 1.0024x; 1.0017x over previous
; #define PG8_STAGE(bufoff, gbase, voff) do { _Pragma("unroll") for (int _i = 0; _i < 2; ++_i) \
;         __builtin_amdgcn_global_load_lds((const unsigned*)((const char*)(gbase) + (voff)[_i]), (PG8_LAS unsigned*)(lds + (bufoff) + ldsw + _i * 8192), 16, 0, 0); } while (0)
; #define PG8_LDA(dst, b, h) do { _Pragma("unroll") for (int m = 0; m < 4; ++m) _Pragma("unroll") for (int k = 0; k < 2; ++k) dst[m][k] = *(const PG8_LAS bf16x8*)(lds + PG8_SA(b, h) + aoff + m * 2048 + k * 1024); } while (0)
; #define PG8_LDB(dst, b, h) do { _Pragma("unroll") for (int n = 0; n < 2; ++n) _Pragma("unroll") for (int k = 0; k < 2; ++k) dst[n][k] = *(const PG8_LAS bf16x8*)(lds + PG8_SB(b, h) + boff + n * 2048 + k * 1024); } while (0)
; #define PG8_MMA(ai, bj, At, Bt) do { __builtin_amdgcn_s_setprio(1); _Pragma("unroll") for (int m = 0; m < 4; ++m) _Pragma("unroll") for (int n = 0; n < 2; ++n) _Pragma("unroll") for (int k = 0; k < 2; ++k) \
;         acc[ai][bj][m][n] = __builtin_amdgcn_mfma_f32_16x16x32_bf16(Bt[n][k], At[m][k], acc[ai][bj][m][n], 0, 0, 0); __builtin_amdgcn_s_setprio(0); } while (0)
; #define PG8_WAIT_V(n) asm volatile("s_waitcnt vmcnt(" #n ")" ::: "memory")
; #define PG8_WAIT_L(n) asm volatile("s_waitcnt lgkmcnt(" #n ")" ::: "memory")
; #define PG8_BAR __builtin_amdgcn_s_barrier()
; #define PG8_SCHED __builtin_amdgcn_sched_barrier(0)
; template <class Epi, class Sched, bool ALIGN_EPI = false, bool SP2 = false>
; __device__ __forceinline__ void gemm_phase(PG8_LAS unsigned char* lds, const Gemm g, const Sched& S, const Epi& E) {
;     ...
;             const bool last = (t == nt - 2);
;             const char* a1 = cA + (size_t)(t + 1) * kstep;
;             const char* a2 = last ? nA : cA + (size_t)(t + 2) * kstep; const char* b2 = last ? nB : cB + (size_t)(t + 2) * kstep;
;             const char* a3 = a2 + kstep; const char* b3 = b2 + kstep;
;             if (last && has_next) S.a_ready(nxt);
;             if constexpr (SP2) {
;             PG8_LDB(B0, 0, 0); PG8_LDB(B1, 0, 1); PG8_SCHED; PG8_LDA(At, 0, 0); PG8_STAGE(PG8_SA(1, 1), a1 + hstep, voffA);
;             PG8_WAIT_V(8); PG8_WAIT_L(0); PG8_BAR; PG8_MMA(0, 0, At, B0); PG8_MMA(0, 1, At, B1); PG8_BAR; PG8_SCHED;
;             PG8_LDA(At, 0, 1); PG8_STAGE(PG8_SB(0, 0), b2, voffB); PG8_STAGE(PG8_SB(0, 1), b2 + hstep, voffB); PG8_STAGE(PG8_SA(0, 0), a2, voffA);
.LBB0_441:
	s_add_i32 s66, 0, 0x10000
	s_add_i32 s67, 0, 0x14000
	v_add_u32_e32 v142, s66, v228
	v_add_u32_e32 v158, s67, v228
	ds_read_b128 v[130:133], v142
	ds_read_b128 v[134:137], v142 offset:1024
	ds_read_b128 v[138:141], v142 offset:2048
	ds_read_b128 v[142:145], v142 offset:3072
	ds_read_b128 v[146:149], v158
	ds_read_b128 v[150:153], v158 offset:1024
	ds_read_b128 v[154:157], v158 offset:2048
	ds_read_b128 v[158:161], v158 offset:3072
	v_lshl_add_u64 v[206:207], s[42:43], 0, v[190:191]
	s_add_i32 m0, s93, 0xc000
	ds_read_b128 v[162:165], v230
	ds_read_b128 v[166:169], v230 offset:1024
	ds_read_b128 v[170:173], v230 offset:2048
	ds_read_b128 v[174:177], v230 offset:3072
	ds_read_b128 v[178:181], v230 offset:4096
	ds_read_b128 v[194:197], v230 offset:5120
	ds_read_b128 v[198:201], v230 offset:6144
	ds_read_b128 v[202:205], v230 offset:7168
	s_add_i32 s61, s44, 2
	s_add_u32 s64, s42, 0x80
	s_addc_u32 s45, s43, 0
	s_cmp_eq_u32 s99, s44
	s_cselect_b32 s45, s29, s45
	s_cselect_b32 s44, s28, s64
	s_cselect_b32 s65, s21, s60
	s_cselect_b32 s64, s20, s17
	global_load_lds_dwordx4 v[206:207], off
	v_lshl_add_u64 v[206:207], s[42:43], 0, v[192:193]
	s_add_i32 m0, s93, 0xe000
	s_nop 0
	global_load_lds_dwordx4 v[206:207], off
	s_setprio 1
	s_waitcnt vmcnt(8) lgkmcnt(0)
	s_barrier
	v_mfma_f32_16x16x32_bf16 v[126:129], v[130:133], v[162:165], v[126:129]
	v_mfma_f32_16x16x32_bf16 v[122:125], v[138:141], v[162:165], v[122:125]
	v_mfma_f32_16x16x32_bf16 v[110:113], v[130:133], v[170:173], v[110:113]
	v_mfma_f32_16x16x32_bf16 v[102:105], v[138:141], v[170:173], v[102:105]
	v_mfma_f32_16x16x32_bf16 v[94:97], v[130:133], v[178:181], v[94:97]
	v_mfma_f32_16x16x32_bf16 v[86:89], v[138:141], v[178:181], v[86:89]
	v_mfma_f32_16x16x32_bf16 v[78:81], v[130:133], v[198:201], v[78:81]
	v_mfma_f32_16x16x32_bf16 v[70:73], v[138:141], v[198:201], v[70:73]
	v_mfma_f32_16x16x32_bf16 v[126:129], v[134:137], v[166:169], v[126:129]
	v_mfma_f32_16x16x32_bf16 v[122:125], v[142:145], v[166:169], v[122:125]
	v_mfma_f32_16x16x32_bf16 v[110:113], v[134:137], v[174:177], v[110:113]
	v_mfma_f32_16x16x32_bf16 v[102:105], v[142:145], v[174:177], v[102:105]
	v_mfma_f32_16x16x32_bf16 v[94:97], v[134:137], v[194:197], v[94:97]
	v_mfma_f32_16x16x32_bf16 v[86:89], v[142:145], v[194:197], v[86:89]
	v_mfma_f32_16x16x32_bf16 v[78:81], v[134:137], v[202:205], v[78:81]
	v_mfma_f32_16x16x32_bf16 v[70:73], v[142:145], v[202:205], v[70:73]
	v_mfma_f32_16x16x32_bf16 v[118:121], v[146:149], v[162:165], v[118:121]
	v_mfma_f32_16x16x32_bf16 v[114:117], v[154:157], v[162:165], v[114:117]
	v_mfma_f32_16x16x32_bf16 v[106:109], v[146:149], v[170:173], v[106:109]
	v_mfma_f32_16x16x32_bf16 v[98:101], v[154:157], v[170:173], v[98:101]
	v_mfma_f32_16x16x32_bf16 v[90:93], v[146:149], v[178:181], v[90:93]
	v_mfma_f32_16x16x32_bf16 v[82:85], v[154:157], v[178:181], v[82:85]
	v_mfma_f32_16x16x32_bf16 v[74:77], v[146:149], v[198:201], v[74:77]
	v_mfma_f32_16x16x32_bf16 v[66:69], v[154:157], v[198:201], v[66:69]
	v_mfma_f32_16x16x32_bf16 v[118:121], v[150:153], v[166:169], v[118:121]
	v_mfma_f32_16x16x32_bf16 v[114:117], v[158:161], v[166:169], v[114:117]
	v_mfma_f32_16x16x32_bf16 v[106:109], v[150:153], v[174:177], v[106:109]
	v_mfma_f32_16x16x32_bf16 v[98:101], v[158:161], v[174:177], v[98:101]
	v_mfma_f32_16x16x32_bf16 v[90:93], v[150:153], v[194:197], v[90:93]
	v_mfma_f32_16x16x32_bf16 v[82:85], v[158:161], v[194:197], v[82:85]
	v_mfma_f32_16x16x32_bf16 v[74:77], v[150:153], v[202:205], v[74:77]
	v_mfma_f32_16x16x32_bf16 v[66:69], v[158:161], v[202:205], v[66:69]
	s_barrier
	s_setprio 0
	ds_read_b128 v[162:165], v230 offset:16384
	ds_read_b128 v[166:169], v230 offset:17408
	ds_read_b128 v[170:173], v230 offset:18432
	ds_read_b128 v[174:177], v230 offset:19456
	ds_read_b128 v[178:181], v230 offset:20480
	ds_read_b128 v[194:197], v230 offset:21504
	ds_read_b128 v[198:201], v230 offset:22528
	ds_read_b128 v[202:205], v230 offset:23552
	s_add_i32 s66, s66, s92
	s_mov_b32 m0, s66
	v_lshl_add_u64 v[206:207], s[64:65], 0, v[184:185]
	global_load_lds_dwordx4 v[206:207], off
	s_add_i32 m0, s66, 0x2000
	v_lshl_add_u64 v[208:209], s[64:65], 0, v[188:189]
	s_add_u32 s64, s64, s26
	s_addc_u32 s65, s65, 0
	s_add_i32 s66, s67, s92
	global_load_lds_dwordx4 v[208:209], off
	v_lshl_add_u64 v[210:211], s[64:65], 0, v[184:185]
	s_mov_b32 m0, s66
	v_lshl_add_u64 v[232:233], s[64:65], 0, v[188:189]
	global_load_lds_dwordx4 v[210:211], off
	s_add_i32 m0, s66, 0x2000
	v_lshl_add_u64 v[234:235], s[44:45], 0, v[182:183]
	global_load_lds_dwordx4 v[232:233], off
	s_mov_b32 m0, s93
	v_lshl_add_u64 v[236:237], s[44:45], 0, v[186:187]
	global_load_lds_dwordx4 v[234:235], off
	s_mov_b32 m0, s94
	s_nop 0
	global_load_lds_dwordx4 v[236:237], off
	s_setprio 1
	s_waitcnt vmcnt(8) lgkmcnt(0)
	s_barrier
; #define PG8_STAGE(bufoff, gbase, voff) do { _Pragma("unroll") for (int _i = 0; _i < 2; ++_i) \
;         __builtin_amdgcn_global_load_lds((const unsigned*)((const char*)(gbase) + (voff)[_i]), (PG8_LAS unsigned*)(lds + (bufoff) + ldsw + _i * 8192), 16, 0, 0); } while (0)
; #define PG8_LDA(dst, b, h) do { _Pragma("unroll") for (int m = 0; m < 4; ++m) _Pragma("unroll") for (int k = 0; k < 2; ++k) dst[m][k] = *(const PG8_LAS bf16x8*)(lds + PG8_SA(b, h) + aoff + m * 2048 + k * 1024); } while (0)
; #define PG8_LDB(dst, b, h) do { _Pragma("unroll") for (int n = 0; n < 2; ++n) _Pragma("unroll") for (int k = 0; k < 2; ++k) dst[n][k] = *(const PG8_LAS bf16x8*)(lds + PG8_SB(b, h) + boff + n * 2048 + k * 1024); } while (0)
; #define PG8_MMA(ai, bj, At, Bt) do { __builtin_amdgcn_s_setprio(1); _Pragma("unroll") for (int m = 0; m < 4; ++m) _Pragma("unroll") for (int n = 0; n < 2; ++n) _Pragma("unroll") for (int k = 0; k < 2; ++k) \
;         acc[ai][bj][m][n] = __builtin_amdgcn_mfma_f32_16x16x32_bf16(Bt[n][k], At[m][k], acc[ai][bj][m][n], 0, 0, 0); __builtin_amdgcn_s_setprio(0); } while (0)
; #define PG8_WAIT_V(n) asm volatile("s_waitcnt vmcnt(" #n ")" ::: "memory")
; #define PG8_WAIT_L(n) asm volatile("s_waitcnt lgkmcnt(" #n ")" ::: "memory")
; #define PG8_BAR __builtin_amdgcn_s_barrier()
; #define PG8_SCHED __builtin_amdgcn_sched_barrier(0)
; template <class Epi, class Sched, bool ALIGN_EPI = false, bool SP2 = false>
; __device__ __forceinline__ void gemm_phase(PG8_LAS unsigned char* lds, const Gemm g, const Sched& S, const Epi& E) {
;     ...
;             PG8_WAIT_V(8); PG8_WAIT_L(0); PG8_BAR; PG8_MMA(1, 0, At, B0); PG8_MMA(1, 1, At, B1); PG8_BAR; PG8_SCHED;
;             PG8_LDB(B0, 1, 0); PG8_LDB(B1, 1, 1); PG8_SCHED; PG8_LDA(At, 1, 0); PG8_STAGE(PG8_SA(0, 1), a2 + hstep, voffA);
;             PG8_WAIT_V(8); PG8_WAIT_L(0); PG8_BAR; PG8_MMA(0, 0, At, B0); PG8_MMA(0, 1, At, B1); PG8_BAR; PG8_SCHED;
	v_mfma_f32_16x16x32_bf16 v[62:65], v[130:133], v[162:165], v[62:65]
	v_mfma_f32_16x16x32_bf16 v[54:57], v[138:141], v[162:165], v[54:57]
	v_mfma_f32_16x16x32_bf16 v[46:49], v[130:133], v[170:173], v[46:49]
	v_mfma_f32_16x16x32_bf16 v[38:41], v[138:141], v[170:173], v[38:41]
	v_mfma_f32_16x16x32_bf16 v[30:33], v[130:133], v[178:181], v[30:33]
	v_mfma_f32_16x16x32_bf16 v[22:25], v[138:141], v[178:181], v[22:25]
	v_mfma_f32_16x16x32_bf16 v[14:17], v[130:133], v[198:201], v[14:17]
	v_mfma_f32_16x16x32_bf16 v[6:9], v[138:141], v[198:201], v[6:9]
	v_mfma_f32_16x16x32_bf16 v[62:65], v[134:137], v[166:169], v[62:65]
	v_mfma_f32_16x16x32_bf16 v[54:57], v[142:145], v[166:169], v[54:57]
	v_mfma_f32_16x16x32_bf16 v[46:49], v[134:137], v[174:177], v[46:49]
	v_mfma_f32_16x16x32_bf16 v[38:41], v[142:145], v[174:177], v[38:41]
	v_mfma_f32_16x16x32_bf16 v[30:33], v[134:137], v[194:197], v[30:33]
	v_mfma_f32_16x16x32_bf16 v[22:25], v[142:145], v[194:197], v[22:25]
	v_mfma_f32_16x16x32_bf16 v[14:17], v[134:137], v[202:205], v[14:17]
	v_mfma_f32_16x16x32_bf16 v[6:9], v[142:145], v[202:205], v[6:9]
	v_mfma_f32_16x16x32_bf16 v[58:61], v[146:149], v[162:165], v[58:61]
	v_mfma_f32_16x16x32_bf16 v[50:53], v[154:157], v[162:165], v[50:53]
	v_mfma_f32_16x16x32_bf16 v[42:45], v[146:149], v[170:173], v[42:45]
	v_mfma_f32_16x16x32_bf16 v[34:37], v[154:157], v[170:173], v[34:37]
	v_mfma_f32_16x16x32_bf16 v[26:29], v[146:149], v[178:181], v[26:29]
	v_mfma_f32_16x16x32_bf16 v[18:21], v[154:157], v[178:181], v[18:21]
	v_mfma_f32_16x16x32_bf16 v[10:13], v[146:149], v[198:201], v[10:13]
	v_mfma_f32_16x16x32_bf16 v[2:5], v[154:157], v[198:201], v[2:5]
	v_mfma_f32_16x16x32_bf16 v[58:61], v[150:153], v[166:169], v[58:61]
	v_mfma_f32_16x16x32_bf16 v[50:53], v[158:161], v[166:169], v[50:53]
	v_mfma_f32_16x16x32_bf16 v[42:45], v[150:153], v[174:177], v[42:45]
	v_mfma_f32_16x16x32_bf16 v[34:37], v[158:161], v[174:177], v[34:37]
	v_mfma_f32_16x16x32_bf16 v[26:29], v[150:153], v[194:197], v[26:29]
	v_mfma_f32_16x16x32_bf16 v[18:21], v[158:161], v[194:197], v[18:21]
	v_mfma_f32_16x16x32_bf16 v[10:13], v[150:153], v[202:205], v[10:13]
	v_mfma_f32_16x16x32_bf16 v[2:5], v[158:161], v[202:205], v[2:5]
	s_barrier
	s_setprio 0
	ds_read_b128 v[162:165], v230 offset:32768
	ds_read_b128 v[166:169], v230 offset:33792
	ds_read_b128 v[170:173], v230 offset:34816
	ds_read_b128 v[174:177], v230 offset:35840
	ds_read_b128 v[178:181], v230 offset:36864
	ds_read_b128 v[194:197], v230 offset:37888
	ds_read_b128 v[198:201], v230 offset:38912
	ds_read_b128 v[202:205], v230 offset:39936
	s_add_i32 s64, 0, 0x18000
	s_add_i32 s65, 0, 0x1c000
	v_add_u32_e32 v142, s64, v228
	v_add_u32_e32 v158, s65, v228
	ds_read_b128 v[130:133], v142
	ds_read_b128 v[134:137], v142 offset:1024
	ds_read_b128 v[138:141], v142 offset:2048
	ds_read_b128 v[142:145], v142 offset:3072
	ds_read_b128 v[146:149], v158
	ds_read_b128 v[150:153], v158 offset:1024
	ds_read_b128 v[154:157], v158 offset:2048
	ds_read_b128 v[158:161], v158 offset:3072
	s_add_u32 s44, s44, s26
	s_addc_u32 s45, s45, 0
	s_mov_b32 m0, s95
	v_lshl_add_u64 v[238:239], s[44:45], 0, v[182:183]
	global_load_lds_dwordx4 v[238:239], off
	v_lshl_add_u64 v[238:239], s[44:45], 0, v[186:187]
	s_mov_b32 m0, s96
	s_nop 0
	global_load_lds_dwordx4 v[238:239], off
	s_setprio 1
	s_waitcnt vmcnt(8) lgkmcnt(0)
	s_barrier
	v_mfma_f32_16x16x32_bf16 v[126:129], v[130:133], v[162:165], v[126:129]
	v_mfma_f32_16x16x32_bf16 v[122:125], v[138:141], v[162:165], v[122:125]
	v_mfma_f32_16x16x32_bf16 v[110:113], v[130:133], v[170:173], v[110:113]
	v_mfma_f32_16x16x32_bf16 v[102:105], v[138:141], v[170:173], v[102:105]
	v_mfma_f32_16x16x32_bf16 v[94:97], v[130:133], v[178:181], v[94:97]
	v_mfma_f32_16x16x32_bf16 v[86:89], v[138:141], v[178:181], v[86:89]
	v_mfma_f32_16x16x32_bf16 v[78:81], v[130:133], v[198:201], v[78:81]
	v_mfma_f32_16x16x32_bf16 v[70:73], v[138:141], v[198:201], v[70:73]
	v_mfma_f32_16x16x32_bf16 v[126:129], v[134:137], v[166:169], v[126:129]
	v_mfma_f32_16x16x32_bf16 v[122:125], v[142:145], v[166:169], v[122:125]
	v_mfma_f32_16x16x32_bf16 v[110:113], v[134:137], v[174:177], v[110:113]
	v_mfma_f32_16x16x32_bf16 v[102:105], v[142:145], v[174:177], v[102:105]
	v_mfma_f32_16x16x32_bf16 v[94:97], v[134:137], v[194:197], v[94:97]
	v_mfma_f32_16x16x32_bf16 v[86:89], v[142:145], v[194:197], v[86:89]
	v_mfma_f32_16x16x32_bf16 v[78:81], v[134:137], v[202:205], v[78:81]
	v_mfma_f32_16x16x32_bf16 v[70:73], v[142:145], v[202:205], v[70:73]
	v_mfma_f32_16x16x32_bf16 v[118:121], v[146:149], v[162:165], v[118:121]
	v_mfma_f32_16x16x32_bf16 v[114:117], v[154:157], v[162:165], v[114:117]
	v_mfma_f32_16x16x32_bf16 v[106:109], v[146:149], v[170:173], v[106:109]
	v_mfma_f32_16x16x32_bf16 v[98:101], v[154:157], v[170:173], v[98:101]
	v_mfma_f32_16x16x32_bf16 v[90:93], v[146:149], v[178:181], v[90:93]
	v_mfma_f32_16x16x32_bf16 v[82:85], v[154:157], v[178:181], v[82:85]
	v_mfma_f32_16x16x32_bf16 v[74:77], v[146:149], v[198:201], v[74:77]
	v_mfma_f32_16x16x32_bf16 v[66:69], v[154:157], v[198:201], v[66:69]
	v_mfma_f32_16x16x32_bf16 v[118:121], v[150:153], v[166:169], v[118:121]
	v_mfma_f32_16x16x32_bf16 v[114:117], v[158:161], v[166:169], v[114:117]
	v_mfma_f32_16x16x32_bf16 v[106:109], v[150:153], v[174:177], v[106:109]
	v_mfma_f32_16x16x32_bf16 v[98:101], v[158:161], v[174:177], v[98:101]
	v_mfma_f32_16x16x32_bf16 v[90:93], v[150:153], v[194:197], v[90:93]
	v_mfma_f32_16x16x32_bf16 v[82:85], v[158:161], v[194:197], v[82:85]
	v_mfma_f32_16x16x32_bf16 v[74:77], v[150:153], v[202:205], v[74:77]
	v_mfma_f32_16x16x32_bf16 v[66:69], v[158:161], v[202:205], v[66:69]
	s_barrier
; #define PG8_STAGE(bufoff, gbase, voff) do { _Pragma("unroll") for (int _i = 0; _i < 2; ++_i) \
;         __builtin_amdgcn_global_load_lds((const unsigned*)((const char*)(gbase) + (voff)[_i]), (PG8_LAS unsigned*)(lds + (bufoff) + ldsw + _i * 8192), 16, 0, 0); } while (0)
; #define PG8_LDA(dst, b, h) do { _Pragma("unroll") for (int m = 0; m < 4; ++m) _Pragma("unroll") for (int k = 0; k < 2; ++k) dst[m][k] = *(const PG8_LAS bf16x8*)(lds + PG8_SA(b, h) + aoff + m * 2048 + k * 1024); } while (0)
; #define PG8_MMA(ai, bj, At, Bt) do { __builtin_amdgcn_s_setprio(1); _Pragma("unroll") for (int m = 0; m < 4; ++m) _Pragma("unroll") for (int n = 0; n < 2; ++n) _Pragma("unroll") for (int k = 0; k < 2; ++k) \
;         acc[ai][bj][m][n] = __builtin_amdgcn_mfma_f32_16x16x32_bf16(Bt[n][k], At[m][k], acc[ai][bj][m][n], 0, 0, 0); __builtin_amdgcn_s_setprio(0); } while (0)
; #define PG8_WAIT_V(n) asm volatile("s_waitcnt vmcnt(" #n ")" ::: "memory")
; #define PG8_WAIT_L(n) asm volatile("s_waitcnt lgkmcnt(" #n ")" ::: "memory")
; #define PG8_BAR __builtin_amdgcn_s_barrier()
; #define PG8_SCHED __builtin_amdgcn_sched_barrier(0)
; template <class Epi, class Sched, bool ALIGN_EPI = false, bool SP2 = false>
; __device__ __forceinline__ void gemm_phase(PG8_LAS unsigned char* lds, const Gemm g, const Sched& S, const Epi& E) {
;     ...
;             PG8_LDA(At, 1, 1); PG8_STAGE(PG8_SB(1, 0), b3, voffB); PG8_STAGE(PG8_SB(1, 1), b3 + hstep, voffB); PG8_STAGE(PG8_SA(1, 0), a3, voffA);
;             PG8_WAIT_V(8); PG8_WAIT_L(0); PG8_BAR; PG8_MMA(1, 0, At, B0); PG8_MMA(1, 1, At, B1); PG8_BAR; PG8_SCHED;
;     ...
;         if constexpr (ALIGN_EPI) { if (wr == 0) PG8_BAR; }
;         if constexpr (!Epi::AFTER_DRAIN) { E(acc, cur, wr, wc, fr, fq); S.done(cur); }
	s_setprio 0
	ds_read_b128 v[162:165], v230 offset:49152
	ds_read_b128 v[166:169], v230 offset:50176
	ds_read_b128 v[170:173], v230 offset:51200
	ds_read_b128 v[174:177], v230 offset:52224
	ds_read_b128 v[178:181], v230 offset:53248
	ds_read_b128 v[194:197], v230 offset:54272
	ds_read_b128 v[198:201], v230 offset:55296
	ds_read_b128 v[202:205], v230 offset:56320
	s_add_i32 s44, s64, s92
	s_mov_b32 m0, s44
	v_lshl_add_u64 v[206:207], v[206:207], 0, s[34:35]
	global_load_lds_dwordx4 v[206:207], off
	v_lshl_add_u64 v[206:207], v[208:209], 0, s[34:35]
	s_add_i32 m0, s44, 0x2000
	s_add_i32 s44, s65, s92
	global_load_lds_dwordx4 v[206:207], off
	v_lshl_add_u64 v[206:207], v[210:211], 0, s[34:35]
	s_mov_b32 m0, s44
	s_nop 0
	global_load_lds_dwordx4 v[206:207], off
	v_lshl_add_u64 v[206:207], v[232:233], 0, s[34:35]
	s_add_i32 m0, s44, 0x2000
	s_nop 0
	global_load_lds_dwordx4 v[206:207], off
	v_lshl_add_u64 v[206:207], v[234:235], 0, s[34:35]
	s_mov_b32 m0, s97
	s_nop 0
	global_load_lds_dwordx4 v[206:207], off
	v_lshl_add_u64 v[206:207], v[236:237], 0, s[34:35]
	s_mov_b32 m0, s98
	s_nop 0
	global_load_lds_dwordx4 v[206:207], off
	s_add_u32 s42, s42, 0x100
	s_addc_u32 s43, s43, 0
	s_add_u32 s17, s17, 0x100
	s_addc_u32 s60, s60, 0
	s_cmp_ge_u32 s61, s4
	s_mov_b32 s44, s61
	s_setprio 1
	s_waitcnt vmcnt(8) lgkmcnt(0)
	s_barrier
	v_mfma_f32_16x16x32_bf16 v[62:65], v[130:133], v[162:165], v[62:65]
	v_mfma_f32_16x16x32_bf16 v[54:57], v[138:141], v[162:165], v[54:57]
	v_mfma_f32_16x16x32_bf16 v[46:49], v[130:133], v[170:173], v[46:49]
	v_mfma_f32_16x16x32_bf16 v[38:41], v[138:141], v[170:173], v[38:41]
	v_mfma_f32_16x16x32_bf16 v[30:33], v[130:133], v[178:181], v[30:33]
	v_mfma_f32_16x16x32_bf16 v[22:25], v[138:141], v[178:181], v[22:25]
	v_mfma_f32_16x16x32_bf16 v[14:17], v[130:133], v[198:201], v[14:17]
	v_mfma_f32_16x16x32_bf16 v[6:9], v[138:141], v[198:201], v[6:9]
	v_mfma_f32_16x16x32_bf16 v[62:65], v[134:137], v[166:169], v[62:65]
	v_mfma_f32_16x16x32_bf16 v[54:57], v[142:145], v[166:169], v[54:57]
	v_mfma_f32_16x16x32_bf16 v[46:49], v[134:137], v[174:177], v[46:49]
	v_mfma_f32_16x16x32_bf16 v[38:41], v[142:145], v[174:177], v[38:41]
	v_mfma_f32_16x16x32_bf16 v[30:33], v[134:137], v[194:197], v[30:33]
	v_mfma_f32_16x16x32_bf16 v[22:25], v[142:145], v[194:197], v[22:25]
	v_mfma_f32_16x16x32_bf16 v[14:17], v[134:137], v[202:205], v[14:17]
	v_mfma_f32_16x16x32_bf16 v[6:9], v[142:145], v[202:205], v[6:9]
	v_mfma_f32_16x16x32_bf16 v[58:61], v[146:149], v[162:165], v[58:61]
	v_mfma_f32_16x16x32_bf16 v[50:53], v[154:157], v[162:165], v[50:53]
	v_mfma_f32_16x16x32_bf16 v[42:45], v[146:149], v[170:173], v[42:45]
	v_mfma_f32_16x16x32_bf16 v[34:37], v[154:157], v[170:173], v[34:37]
	v_mfma_f32_16x16x32_bf16 v[26:29], v[146:149], v[178:181], v[26:29]
	v_mfma_f32_16x16x32_bf16 v[18:21], v[154:157], v[178:181], v[18:21]
	v_mfma_f32_16x16x32_bf16 v[10:13], v[146:149], v[198:201], v[10:13]
	v_mfma_f32_16x16x32_bf16 v[2:5], v[154:157], v[198:201], v[2:5]
	v_mfma_f32_16x16x32_bf16 v[58:61], v[150:153], v[166:169], v[58:61]
	v_mfma_f32_16x16x32_bf16 v[50:53], v[158:161], v[166:169], v[50:53]
	v_mfma_f32_16x16x32_bf16 v[42:45], v[150:153], v[174:177], v[42:45]
	v_mfma_f32_16x16x32_bf16 v[34:37], v[158:161], v[174:177], v[34:37]
	v_mfma_f32_16x16x32_bf16 v[26:29], v[150:153], v[194:197], v[26:29]
	v_mfma_f32_16x16x32_bf16 v[18:21], v[158:161], v[194:197], v[18:21]
	v_mfma_f32_16x16x32_bf16 v[10:13], v[150:153], v[202:205], v[10:13]
	v_mfma_f32_16x16x32_bf16 v[2:5], v[158:161], v[202:205], v[2:5]
	s_barrier
	s_setprio 0
	s_cbranch_scc0 .LBB0_441
	s_and_b64 vcc, exec, s[36:37]
	s_cbranch_vccz .LBB0_445
	s_barrier
	s_cmp_lt_i32 s0, 2
	s_mov_b64 s[42:43], -1
	s_cbranch_scc0 .LBB0_446
